# seam 0: the sixteen census loads issued together instead of one round trip each
# baseline (speedup 1.0000x reference)
; __device__ __forceinline__ unsigned xb_ld(unsigned* p)              { return __hip_atomic_load(p, __ATOMIC_RELAXED, __HIP_MEMORY_SCOPE_AGENT); }
; __device__ __forceinline__ void xcd_barrier_complete(unsigned* bar, unsigned x, unsigned& nloc, unsigned& nx) {
;     ...
;     unsigned sum, cnt, mine, sp = 0u;
;     for (;;) {
;         sum = 0u; cnt = 0u; mine = 0u;
; #pragma unroll
;         for (unsigned j = 0; j < 16; ++j) { const unsigned c = xb_ld(&bar[XB_XCNT(j)]); sum += c; cnt += (c > 0u) ? 1u : 0u; mine = (j == x) ? c : mine; }
;         if (sum == G) break;
.Lg0_census:
	s_mov_b32 s13, 0
	s_mov_b32 s14, 0
	s_mov_b32 s17, 0
	v_mov_b32_e32 v0, 0x400
	global_load_dword v100, v0, s[4:5] sc1
	global_load_dword v101, v0, s[4:5] offset:256 sc1
	global_load_dword v102, v0, s[4:5] offset:512 sc1
	global_load_dword v103, v0, s[4:5] offset:768 sc1
	global_load_dword v104, v0, s[4:5] offset:1024 sc1
	global_load_dword v105, v0, s[4:5] offset:1280 sc1
	global_load_dword v106, v0, s[4:5] offset:1536 sc1
	global_load_dword v107, v0, s[4:5] offset:1792 sc1
	global_load_dword v108, v0, s[4:5] offset:2048 sc1
	global_load_dword v109, v0, s[4:5] offset:2304 sc1
	global_load_dword v110, v0, s[4:5] offset:2560 sc1
	global_load_dword v111, v0, s[4:5] offset:2816 sc1
	global_load_dword v112, v0, s[4:5] offset:3072 sc1
	global_load_dword v113, v0, s[4:5] offset:3328 sc1
	global_load_dword v114, v0, s[4:5] offset:3584 sc1
	global_load_dword v115, v0, s[4:5] offset:3840 sc1
	s_waitcnt vmcnt(0)
	v_readfirstlane_b32 s16, v100
	s_add_i32 s13, s13, s16
	s_cmp_eq_u32 s10, 0
	s_cselect_b32 s14, s16, s14
	s_cmp_lg_u32 s16, 0
	s_cselect_b32 s9, 1, 0
	s_add_i32 s17, s17, s9
	v_readfirstlane_b32 s16, v101
	s_add_i32 s13, s13, s16
	s_cmp_eq_u32 s10, 1
	s_cselect_b32 s14, s16, s14
	s_cmp_lg_u32 s16, 0
	s_cselect_b32 s9, 1, 0
	s_add_i32 s17, s17, s9
	v_readfirstlane_b32 s16, v102
	s_add_i32 s13, s13, s16
	s_cmp_eq_u32 s10, 2
	s_cselect_b32 s14, s16, s14
	s_cmp_lg_u32 s16, 0
	s_cselect_b32 s9, 1, 0
	s_add_i32 s17, s17, s9
	v_readfirstlane_b32 s16, v103
	s_add_i32 s13, s13, s16
	s_cmp_eq_u32 s10, 3
	s_cselect_b32 s14, s16, s14
	s_cmp_lg_u32 s16, 0
	s_cselect_b32 s9, 1, 0
	s_add_i32 s17, s17, s9
	v_readfirstlane_b32 s16, v104
	s_add_i32 s13, s13, s16
	s_cmp_eq_u32 s10, 4
	s_cselect_b32 s14, s16, s14
	s_cmp_lg_u32 s16, 0
	s_cselect_b32 s9, 1, 0
	s_add_i32 s17, s17, s9
	v_readfirstlane_b32 s16, v105
	s_add_i32 s13, s13, s16
	s_cmp_eq_u32 s10, 5
	s_cselect_b32 s14, s16, s14
	s_cmp_lg_u32 s16, 0
	s_cselect_b32 s9, 1, 0
	s_add_i32 s17, s17, s9
	v_readfirstlane_b32 s16, v106
	s_add_i32 s13, s13, s16
	s_cmp_eq_u32 s10, 6
	s_cselect_b32 s14, s16, s14
	s_cmp_lg_u32 s16, 0
	s_cselect_b32 s9, 1, 0
	s_add_i32 s17, s17, s9
	v_readfirstlane_b32 s16, v107
	s_add_i32 s13, s13, s16
	s_cmp_eq_u32 s10, 7
	s_cselect_b32 s14, s16, s14
	s_cmp_lg_u32 s16, 0
	s_cselect_b32 s9, 1, 0
	s_add_i32 s17, s17, s9
	v_readfirstlane_b32 s16, v108
	s_add_i32 s13, s13, s16
	s_cmp_eq_u32 s10, 8
	s_cselect_b32 s14, s16, s14
	s_cmp_lg_u32 s16, 0
	s_cselect_b32 s9, 1, 0
	s_add_i32 s17, s17, s9
	v_readfirstlane_b32 s16, v109
	s_add_i32 s13, s13, s16
	s_cmp_eq_u32 s10, 9
	s_cselect_b32 s14, s16, s14
	s_cmp_lg_u32 s16, 0
	s_cselect_b32 s9, 1, 0
	s_add_i32 s17, s17, s9
	v_readfirstlane_b32 s16, v110
	s_add_i32 s13, s13, s16
	s_cmp_eq_u32 s10, 10
	s_cselect_b32 s14, s16, s14
	s_cmp_lg_u32 s16, 0
	s_cselect_b32 s9, 1, 0
	s_add_i32 s17, s17, s9
	v_readfirstlane_b32 s16, v111
	s_add_i32 s13, s13, s16
	s_cmp_eq_u32 s10, 11
	s_cselect_b32 s14, s16, s14
	s_cmp_lg_u32 s16, 0
	s_cselect_b32 s9, 1, 0
	s_add_i32 s17, s17, s9
	v_readfirstlane_b32 s16, v112
	s_add_i32 s13, s13, s16
	s_cmp_eq_u32 s10, 12
	s_cselect_b32 s14, s16, s14
	s_cmp_lg_u32 s16, 0
	s_cselect_b32 s9, 1, 0
	s_add_i32 s17, s17, s9
	v_readfirstlane_b32 s16, v113
	s_add_i32 s13, s13, s16
	s_cmp_eq_u32 s10, 13
	s_cselect_b32 s14, s16, s14
	s_cmp_lg_u32 s16, 0
	s_cselect_b32 s9, 1, 0
	s_add_i32 s17, s17, s9
	v_readfirstlane_b32 s16, v114
	s_add_i32 s13, s13, s16
	s_cmp_eq_u32 s10, 14
	s_cselect_b32 s14, s16, s14
	s_cmp_lg_u32 s16, 0
	s_cselect_b32 s9, 1, 0
	s_add_i32 s17, s17, s9
	v_readfirstlane_b32 s16, v115
	s_add_i32 s13, s13, s16
	s_cmp_eq_u32 s10, 15
	s_cselect_b32 s14, s16, s14
	s_cmp_lg_u32 s16, 0
	s_cselect_b32 s9, 1, 0
	s_add_i32 s17, s17, s9
	s_cmp_eq_u32 s13, s34
	s_cbranch_scc1 .Lg0_pub
	s_sleep 1
	s_add_i32 s11, s11, 1
	s_cmp_lt_u32 s11, 0x4000
	s_cbranch_scc1 .Lg0_census
	s_branch .Lg0_arrive
